# NA: all 16 K/V tiles of an item staged by LDS-DMA ring (tiles 0-2 issued at item start) plus early epilogue gate loads; later code 8 bytes off the v138 placement
# speedup vs baseline: 1.0044x; 1.0026x over previous
.LBB0_160:
	s_andn2_b64 vcc, exec, s[4:5]
	s_cbranch_vccnz .LBB0_267
	s_cmp_eq_u32 s81, 0
	s_movk_i32 s2, 0x800
	s_cselect_b32 s69, s2, 0x840
	s_cmp_ge_i32 s72, s69
	s_cbranch_scc1 .LBB0_267
	v_ashrrev_i32_e32 v7, 1, v178
	s_movk_i32 s2, 0xffe0
	v_bfi_b32 v4, s2, v7, v178
	v_ashrrev_i32_e32 v5, 31, v4
	v_lshlrev_b32_e32 v3, 3, v178
	v_lshlrev_b64 v[110:111], 13, v[4:5]
	v_ashrrev_i32_e32 v114, 3, v178
	v_ashrrev_i32_e32 v118, 5, v178
	v_bfe_u32 v4, v3, 5, 1
	s_mov_b32 s2, 0x7ffffe
	v_and_or_b32 v4, v118, s2, v4
	v_lshlrev_b32_e32 v5, 5, v114
	v_and_b32_e32 v8, 24, v3
	s_movk_i32 s2, 0xe0
	v_and_or_b32 v5, v5, s2, v8
	s_add_u32 s89, s98, 0x4600000
	v_and_b32_e32 v116, 56, v3
	v_lshlrev_b32_e32 v4, 9, v4
	v_lshlrev_b32_e32 v5, 1, v5
	s_addc_u32 s26, s99, 0
	v_add3_u32 v113, 16, v4, v5
	v_lshlrev_b32_e32 v5, 1, v116
	v_lshlrev_b32_e32 v8, 4, v114
	s_movk_i32 s2, 0x70
	s_add_u32 s27, s98, 0x4600800
	v_lshlrev_b32_e32 v4, 7, v114
	v_bitop3_b32 v5, v5, v8, s2 bitop3:0x78
	s_addc_u32 s28, s99, 0
	v_add3_u32 v117, 16, v5, v4
	v_lshlrev_b32_e32 v4, 1, v178
	s_add_u32 s29, s98, 0x4601000
	v_bfe_u32 v6, v178, 5, 1
	v_and_b32_e32 v4, 32, v4
	s_movk_i32 s4, 0x118
	s_addc_u32 s36, s99, 0
	v_and_or_b32 v3, v3, s4, v4
	v_lshlrev_b32_e32 v4, 4, v178
	v_lshlrev_b32_e32 v119, 4, v6
	v_and_b32_e32 v0, 0x3fffffc0, v178
	v_and_b32_e32 v8, 0x70, v4
	v_bitop3_b32 v130, v119, v4, s2 bitop3:0x78
	s_movk_i32 s2, 0x60
	s_cmp_lg_u32 16, -1
	v_lshl_add_u32 v109, v0, 2, 16
	v_and_b32_e32 v0, 63, v178
	v_and_b32_e32 v2, 0xffffffe0, v7
	v_and_b32_e32 v5, 0xc0, v4
	v_bitop3_b32 v133, v119, v8, s2 bitop3:0x36
	s_cselect_b32 s2, 16, 0
	v_and_b32_e32 v108, 31, v178
	v_cmp_gt_u32_e64 s[76:77], 32, v0
	v_add3_u32 v135, v5, s2, v3
	v_ashrrev_i32_e32 v3, 31, v2
	v_and_b32_e32 v0, 32, v7
	v_writelane_b32 v254, s34, 18
	v_lshlrev_b64 v[120:121], 13, v[2:3]
	v_or_b32_e32 v2, v0, v108
	v_writelane_b32 v254, s35, 19
	s_lshl_b64 s[4:5], 1, s47
	v_cmp_ne_u32_e64 s[8:9], 31, v108
	v_med3_u32 v2, v2, 8, 56
	v_lshlrev_b32_e32 v5, 2, v6
	v_lshlrev_b32_e32 v112, 3, v6
	s_and_b32 s92, s4, 0xfff72ef6
	v_lshlrev_b32_e32 v122, 15, v6
	v_writelane_b32 v254, s8, 20
	v_add_u32_e32 v3, -8, v2
	v_add_u32_e32 v4, 8, v2
	v_subrev_u32_e32 v2, 24, v2
	v_or_b32_e32 v6, 32, v5
	s_cmp_lg_u64 s[92:93], 0
	v_writelane_b32 v254, s9, 21
	v_cmp_ge_u32_e32 vcc, v6, v3
	v_cmp_lt_i32_e64 s[8:9], v5, v2
	s_cselect_b64 s[6:7], -1, 0
	s_and_b64 s[8:9], vcc, s[8:9]
	v_writelane_b32 v254, s8, 22
	v_or_b32_e32 v6, 1, v5
	v_or_b32_e32 v7, 33, v5
	v_writelane_b32 v254, s9, 23
	v_cmp_lt_u32_e64 s[8:9], v6, v3
	v_cmp_ge_u32_e32 vcc, v7, v3
	v_cmp_lt_i32_e64 s[14:15], v6, v2
	v_writelane_b32 v254, s8, 24
	v_or_b32_e32 v6, 34, v5
	v_or_b32_e32 v7, 2, v5
	v_writelane_b32 v254, s9, 25
	v_cmp_lt_u32_e64 s[8:9], v5, v3
	v_cmp_lt_i32_e64 s[16:17], v7, v2
	v_bitop3_b32 v131, v119, v8, 32 bitop3:0x36
	v_writelane_b32 v254, s8, 26
	v_bitop3_b32 v132, v119, v8, 64 bitop3:0x36
	v_or_b32_e32 v8, 35, v5
	v_writelane_b32 v254, s9, 27
	s_and_b64 s[8:9], vcc, s[14:15]
	v_writelane_b32 v254, s8, 28
	v_cmp_ge_u32_e32 vcc, v6, v3
	v_or_b32_e32 v6, 3, v5
	v_writelane_b32 v254, s9, 29
	s_and_b64 s[8:9], vcc, s[16:17]
	v_writelane_b32 v254, s8, 30
	v_cmp_ge_u32_e32 vcc, v8, v3
	v_cmp_lt_i32_e64 s[22:23], v6, v2
	v_writelane_b32 v254, s9, 31
	v_cmp_lt_u32_e64 s[8:9], v6, v3
	v_or_b32_e32 v8, 40, v5
	v_or_b32_e32 v9, 8, v5
	v_writelane_b32 v254, s8, 32
	v_cmp_lt_i32_e64 s[24:25], v9, v2
	v_or_b32_e32 v10, 41, v5
	v_writelane_b32 v254, s9, 33
	v_cmp_lt_u32_e64 s[8:9], v7, v3
	v_or_b32_e32 v11, 10, v5
	v_cmp_lt_i32_e64 s[34:35], v11, v2
	v_writelane_b32 v254, s8, 34
	v_or_b32_e32 v12, 43, v5
	v_or_b32_e32 v13, 16, v5
	v_writelane_b32 v254, s9, 35
	s_and_b64 s[8:9], vcc, s[22:23]
	v_writelane_b32 v254, s8, 36
	v_cmp_ge_u32_e32 vcc, v8, v3
	v_or_b32_e32 v8, 9, v5
	v_writelane_b32 v254, s9, 37
	s_and_b64 s[8:9], vcc, s[24:25]
	v_writelane_b32 v254, s8, 38
	v_cmp_ge_u32_e32 vcc, v10, v3
	v_cmp_lt_i32_e64 s[30:31], v8, v2
	v_writelane_b32 v254, s9, 39
	v_cmp_lt_u32_e64 s[8:9], v8, v3
	v_or_b32_e32 v10, 42, v5
	v_cmp_lt_u32_e64 s[42:43], v13, v4
	v_writelane_b32 v254, s8, 40
	v_or_b32_e32 v15, 18, v5
	v_or_b32_e32 v14, 19, v5
	v_writelane_b32 v254, s9, 41
	v_cmp_lt_u32_e64 s[8:9], v9, v3
	v_cmp_lt_u32_e64 s[50:51], v15, v4
	v_cmp_lt_u32_e64 s[52:53], v14, v4
	v_writelane_b32 v254, s8, 42
	v_or_b32_e32 v17, 24, v5
	v_or_b32_e32 v16, 25, v5
	v_writelane_b32 v254, s9, 43
	s_and_b64 s[8:9], vcc, s[30:31]
	v_writelane_b32 v254, s8, 44
	v_cmp_ge_u32_e32 vcc, v10, v3
	v_or_b32_e32 v10, 11, v5
	v_writelane_b32 v254, s9, 45
	s_and_b64 s[8:9], vcc, s[34:35]
	v_writelane_b32 v254, s8, 46
	v_cmp_ge_u32_e32 vcc, v12, v3
	v_cmp_lt_i32_e64 s[40:41], v10, v2
	v_writelane_b32 v254, s9, 47
	v_cmp_lt_u32_e64 s[8:9], v10, v3
	v_or_b32_e32 v12, 17, v5
	v_cmp_lt_u32_e64 s[44:45], v12, v4
	v_writelane_b32 v254, s8, 48
	v_cmp_lt_u32_e64 s[58:59], v17, v4
	v_cmp_lt_u32_e64 s[60:61], v16, v4
	v_writelane_b32 v254, s9, 49
	v_cmp_lt_u32_e64 s[8:9], v11, v3
	v_or_b32_e32 v18, 26, v5
	v_cmp_lt_u32_e64 s[66:67], v18, v4
	v_writelane_b32 v254, s8, 50
	v_cmp_lt_i32_e64 s[22:23], v18, v2
	v_cmp_lt_i32_e64 s[10:11], v12, v2
	v_writelane_b32 v254, s9, 51
	s_and_b64 s[8:9], vcc, s[40:41]
	v_writelane_b32 v254, s8, 52
	v_cmp_ge_u32_e32 vcc, v13, v3
	v_cmp_lt_i32_e64 s[12:13], v13, v2
	v_writelane_b32 v254, s9, 53
	s_and_b64 s[8:9], vcc, s[42:43]
	v_cmp_ge_u32_e32 vcc, v12, v3
	s_and_b64 s[44:45], vcc, s[44:45]
	v_cmp_ge_u32_e32 vcc, v15, v3
	s_and_b64 s[50:51], vcc, s[50:51]
	v_cmp_ge_u32_e32 vcc, v14, v3
	s_and_b64 s[52:53], vcc, s[52:53]
	v_cmp_ge_u32_e32 vcc, v17, v3
	s_and_b64 s[58:59], vcc, s[58:59]
	v_cmp_ge_u32_e32 vcc, v16, v3
	s_and_b64 s[60:61], vcc, s[60:61]
	v_cmp_ge_u32_e32 vcc, v18, v3
	v_or_b32_e32 v18, 27, v5
	v_cmp_lt_i32_e64 s[14:15], v14, v2
	v_cmp_lt_i32_e64 s[16:17], v15, v2
	v_cmp_lt_i32_e64 s[18:19], v16, v2
	v_cmp_lt_i32_e64 s[20:21], v17, v2
	v_cmp_lt_i32_e64 s[30:31], v18, v2
	v_sub_u32_e32 v2, v5, v108
	v_sub_u32_e32 v2, v2, v0
	s_and_b64 s[66:67], vcc, s[66:67]
	v_cmp_ge_u32_e32 vcc, v18, v3
	v_add_u32_e32 v3, 59, v2
	v_min_i32_e32 v3, 15, v3
	v_lshlrev_b32_e32 v140, 2, v3
	v_and_b32_e32 v3, 0xffffff80, v178
	v_sub_u32_e32 v141, 16, v3
	v_add_u32_e32 v3, 27, v2
	v_med3_i32 v3, v3, -15, 15
	v_lshlrev_b32_e32 v142, 2, v3
	v_add_u32_e32 v3, 58, v2
	v_min_i32_e32 v3, 15, v3
	v_lshlrev_b32_e32 v143, 2, v3
	v_add_u32_e32 v3, 26, v2
	v_med3_i32 v3, v3, -15, 15
	v_lshlrev_b32_e32 v144, 2, v3
	v_add_u32_e32 v3, 57, v2
	v_min_i32_e32 v3, 15, v3
	v_lshlrev_b32_e32 v145, 2, v3
	v_sub_u32_e32 v3, v16, v108
	v_sub_u32_e32 v3, v3, v0
	v_med3_i32 v3, v3, -15, 15
	v_lshlrev_b32_e32 v146, 2, v3
	v_add_u32_e32 v3, 56, v2
	v_min_i32_e32 v3, 15, v3
	v_lshlrev_b32_e32 v147, 2, v3
	v_sub_u32_e32 v3, v17, v108
	v_sub_u32_e32 v3, v3, v0
	v_med3_i32 v3, v3, -15, 15
	v_lshlrev_b32_e32 v148, 2, v3
	v_add_u32_e32 v3, 51, v2
	v_min_i32_e32 v3, 15, v3
	v_lshlrev_b32_e32 v149, 2, v3
	v_sub_u32_e32 v3, v14, v108
	v_sub_u32_e32 v3, v3, v0
	v_med3_i32 v3, v3, -15, 15
	v_lshlrev_b32_e32 v150, 2, v3
	v_add_u32_e32 v3, 50, v2
	v_min_i32_e32 v3, 15, v3
	v_lshlrev_b32_e32 v151, 2, v3
	v_sub_u32_e32 v3, v15, v108
	v_sub_u32_e32 v3, v3, v0
	v_med3_i32 v3, v3, -15, 15
	v_lshlrev_b32_e32 v152, 2, v3
	v_add_u32_e32 v3, 49, v2
	v_min_i32_e32 v3, 15, v3
	v_lshlrev_b32_e32 v153, 2, v3
	v_sub_u32_e32 v3, v12, v108
	v_sub_u32_e32 v3, v3, v0
	v_med3_i32 v3, v3, -15, 15
	v_lshlrev_b32_e32 v154, 2, v3
	v_add_u32_e32 v3, 48, v2
	v_min_i32_e32 v3, 15, v3
	v_lshlrev_b32_e32 v155, 2, v3
	v_sub_u32_e32 v3, v13, v108
	v_sub_u32_e32 v3, v3, v0
	v_med3_i32 v3, v3, -15, 15
	v_lshlrev_b32_e32 v156, 2, v3
	v_add_u32_e32 v3, 43, v2
	v_med3_i32 v3, v3, -15, 15
	v_lshlrev_b32_e32 v157, 2, v3
	v_sub_u32_e32 v3, v10, v108
	v_sub_u32_e32 v3, v3, v0
	v_max_i32_e32 v3, -15, v3
	v_lshlrev_b32_e32 v158, 2, v3
	v_add_u32_e32 v3, 42, v2
	v_med3_i32 v3, v3, -15, 15
	v_lshlrev_b32_e32 v159, 2, v3
	v_sub_u32_e32 v3, v11, v108
	v_sub_u32_e32 v3, v3, v0
	v_max_i32_e32 v3, -15, v3
	v_lshlrev_b32_e32 v160, 2, v3
	v_add_u32_e32 v3, 41, v2
	v_med3_i32 v3, v3, -15, 15
	v_lshlrev_b32_e32 v161, 2, v3
	v_sub_u32_e32 v3, v8, v108
	v_sub_u32_e32 v3, v3, v0
	v_max_i32_e32 v3, -15, v3
	v_lshlrev_b32_e32 v162, 2, v3
	v_add_u32_e32 v3, 40, v2
	v_med3_i32 v3, v3, -15, 15
	v_lshlrev_b32_e32 v163, 2, v3
	v_sub_u32_e32 v3, v9, v108
	v_sub_u32_e32 v3, v3, v0
	v_max_i32_e32 v3, -15, v3
	v_lshlrev_b32_e32 v164, 2, v3
	v_add_u32_e32 v3, 35, v2
	v_med3_i32 v3, v3, -15, 15
	v_lshlrev_b32_e32 v165, 2, v3
	v_sub_u32_e32 v3, v6, v108
	v_sub_u32_e32 v3, v3, v0
	v_max_i32_e32 v3, -15, v3
	v_lshlrev_b32_e32 v166, 2, v3
	v_add_u32_e32 v3, 34, v2
	v_med3_i32 v3, v3, -15, 15
	v_lshlrev_b32_e32 v167, 2, v3
	v_sub_u32_e32 v3, v7, v108
	v_sub_u32_e32 v0, v3, v0
	v_max_i32_e32 v0, -15, v0
	v_lshlrev_b32_e32 v168, 2, v0
	v_add_u32_e32 v0, 33, v2
	v_med3_i32 v0, v0, -15, 15
	v_lshlrev_b32_e32 v169, 2, v0
	v_add_u32_e32 v0, 1, v2
	v_max_i32_e32 v0, -15, v0
	v_lshlrev_b32_e32 v170, 2, v0
	v_add_u32_e32 v0, 32, v2
	v_writelane_b32 v254, s8, 54
	v_med3_i32 v0, v0, -15, 15
	s_movk_i32 s2, 0x1e0
	v_writelane_b32 v254, s9, 55
	v_cmp_lt_u32_e64 s[70:71], v18, v4
	v_lshlrev_b32_e32 v171, 2, v0
	v_max_i32_e32 v0, -15, v2
	v_ashrrev_i32_e32 v115, 31, v114
	v_lshl_add_u32 v134, v108, 2, v109
	v_lshl_add_u32 v136, v108, 7, 16
	v_ashrrev_i32_e32 v179, 31, v178
	v_mov_b32_e32 v123, v1
	v_cmp_gt_i32_e64 s[4:5], s2, v178
	v_lshl_add_u32 v137, v178, 2, 16
	v_ashrrev_i32_e32 v138, 7, v178
	s_mov_b32 s43, 0x14000
	s_movk_i32 s42, 0x2000
	s_and_b64 s[70:71], vcc, s[70:71]
	v_add_u32_e32 v139, 0x2000, v135
	v_lshlrev_b32_e32 v172, 2, v0
	v_readlane_b32 s37, v254, 7
	s_mov_b32 s2, s72
	v_and_b32_e32 v2, 63, v178
	v_lshrrev_b32_e32 v3, 6, v178
	v_lshrrev_b32_e32 v4, 3, v2
	s_nop 0
	v_readfirstlane_b32 s32, v3
	v_lshlrev_b32_e32 v3, 16, v3
	v_and_b32_e32 v5, 7, v2
	v_xor_b32_e32 v5, v5, v4
	v_lshlrev_b32_e32 v5, 4, v5
	v_lshl_add_u32 v5, v4, 13, v5
	v_add_u32_e32 v220, v3, v5
	v_and_b32_e32 v4, 31, v2
	v_lshrrev_b32_e32 v4, 2, v4
	v_lshrrev_b32_e32 v5, 5, v2
	v_lshlrev_b32_e32 v5, 6, v5
	v_lshl_add_u32 v5, v4, 13, v5
	v_and_b32_e32 v4, 3, v2
	v_lshl_add_u32 v5, v4, 4, v5
	v_add_u32_e32 v221, v3, v5
	v_add_u32_e32 v221, 0x800, v221
	s_lshl_b32 s32, s32, 10
	s_add_i32 s32, s32, 16
	v_add_u32_e32 v222, v136, v130
	v_add_u32_e32 v223, v136, v131
	v_add_u32_e32 v224, v136, v132
	v_add_u32_e32 v225, v136, v133
	v_add_u32_e32 v222, 0xa000, v222
	v_add_u32_e32 v223, 0xa000, v223
	v_add_u32_e32 v224, 0xa000, v224
	v_add_u32_e32 v225, 0xa000, v225
	v_add_u32_e32 v226, 0xa000, v135
	v_add_u32_e32 v227, 0xa000, v139
	s_branch .LBB0_165

.LBB0_194:
	s_and_b64 vcc, exec, s[8:9]
	s_cbranch_vccz .LBB0_164
	s_and_b32 s92, s2, 15
	s_ashr_i32 s41, s2, 9
	s_mulk_i32 s41, 0x2100
	s_add_i32 s41, s41, 0
	s_lshl_b32 s41, s41, 13
	s_and_b32 s40, s2, 15
	s_lshl_b32 s40, s40, 7
	s_add_u32 s38, s27, s40
	s_addc_u32 s39, s28, 0
	s_add_u32 s38, s38, s41
	s_addc_u32 s39, s39, 0
	s_add_i32 s40, s32, 0x0
	s_mov_b32 m0, s40
	s_nop 0
	global_load_lds_dwordx4 v221, s[38:39]
	s_add_i32 m0, s40, 0x4000
	s_nop 0
	global_load_lds_dwordx4 v220, s[38:39]
	s_ashr_i32 s41, s2, 9
	s_mulk_i32 s41, 0x2100
	s_add_i32 s41, s41, 64
	s_lshl_b32 s41, s41, 13
	s_and_b32 s40, s2, 15
	s_lshl_b32 s40, s40, 7
	s_add_u32 s38, s27, s40
	s_addc_u32 s39, s28, 0
	s_add_u32 s38, s38, s41
	s_addc_u32 s39, s39, 0
	s_add_i32 s40, s32, 0x2000
	s_mov_b32 m0, s40
	s_nop 0
	global_load_lds_dwordx4 v221, s[38:39]
	s_add_i32 m0, s40, 0x4000
	s_nop 0
	global_load_lds_dwordx4 v220, s[38:39]
	s_ashr_i32 s41, s2, 9
	s_mulk_i32 s41, 0x2100
	s_add_i32 s41, s41, 128
	s_lshl_b32 s41, s41, 13
	s_and_b32 s40, s2, 15
	s_lshl_b32 s40, s40, 7
	s_add_u32 s38, s27, s40
	s_addc_u32 s39, s28, 0
	s_add_u32 s38, s38, s41
	s_addc_u32 s39, s39, 0
	s_add_i32 s40, s32, 0xa000
	s_mov_b32 m0, s40
	s_nop 0
	global_load_lds_dwordx4 v221, s[38:39]
	s_add_i32 m0, s40, 0x4000
	s_nop 0
	global_load_lds_dwordx4 v220, s[38:39]
	s_and_saveexec_b64 s[8:9], s[4:5]
	s_cbranch_execz .LBB0_199
	v_mov_b32_e32 v2, 0
	s_mov_b64 s[74:75], exec
	v_readlane_b32 s24, v254, 20
	v_readlane_b32 s25, v254, 21
	s_and_b64 s[24:25], s[74:75], s[24:25]
	s_mov_b64 exec, s[24:25]
	s_cbranch_execz .LBB0_198
	s_load_dwordx2 s[24:25], s[0:1], 0x68
	v_mad_u64_u32 v[2:3], s[34:35], s92, 15, v[118:119]
	v_mad_u64_u32 v[2:3], s[34:35], v2, 31, v[108:109]
	v_ashrrev_i32_e32 v3, 31, v2
	s_waitcnt lgkmcnt(0)
	v_lshl_add_u64 v[2:3], v[2:3], 2, s[24:25]
	global_load_dword v2, v[2:3], off
	s_waitcnt vmcnt(0)
	v_mul_f32_e32 v2, 0x3fb8aa3b, v2

.LBB0_199:
	s_or_b64 exec, exec, s[8:9]
	s_ashr_i32 s8, s2, 9
	s_lshr_b32 s9, s2, 2
	s_and_b32 s24, s9, 0x7c
	s_mulk_i32 s8, 0x2100
	s_add_i32 s25, s8, 0x100
	s_lshl_b32 s9, s24, 6
	s_add_i32 s34, s25, s9
	s_ashr_i32 s35, s34, 31
	s_lshl_b64 s[34:35], s[34:35], 13
	s_add_u32 s34, s89, s34
	s_addc_u32 s35, s26, s35
	s_lshl_b32 s9, s92, 7
	s_add_u32 s38, s34, s9
	s_addc_u32 s39, s35, 0
	v_lshl_add_u64 v[2:3], s[38:39], 0, v[110:111]
	v_mov_b32_e32 v107, v1
	v_lshl_add_u64 v[14:15], v[2:3], 0, v[106:107]
	global_load_dwordx4 v[2:5], v[14:15], off
	global_load_dwordx4 v[6:9], v[14:15], off offset:32
	global_load_dwordx4 v[10:13], v[14:15], off offset:64
	s_nop 0
	global_load_dwordx4 v[14:17], v[14:15], off offset:96
	s_add_u32 vcc_lo, s27, s9
	s_addc_u32 vcc_hi, s28, 0
	s_add_u32 s74, s29, s9
	s_addc_u32 s75, s36, 0
	s_ashr_i32 s9, s8, 31
	s_cmp_lt_i32 s73, 1
	s_waitcnt vmcnt(3)
	v_lshlrev_b32_e32 v18, 16, v2
	v_and_b32_e32 v2, 0xffff0000, v2
	v_lshlrev_b32_e32 v19, 16, v3
	v_and_b32_e32 v3, 0xffff0000, v3
	v_lshlrev_b32_e32 v20, 16, v4
	v_and_b32_e32 v4, 0xffff0000, v4
	v_mul_f32_e32 v2, 0x3e38aa3b, v2
	v_mul_f32_e32 v3, 0x3e38aa3b, v3
	v_mul_f32_e32 v18, 0x3e38aa3b, v18
	v_mul_f32_e32 v19, 0x3e38aa3b, v19
	v_mul_f32_e32 v4, 0x3e38aa3b, v4
	v_cvt_pk_bf16_f32 v84, v18, v2
	v_cvt_pk_bf16_f32 v85, v19, v3
	s_waitcnt vmcnt(0)
	v_and_b32_e32 v2, 0xffff0000, v16
	v_lshlrev_b32_e32 v3, 16, v17
	v_lshlrev_b32_e32 v21, 16, v5
	v_and_b32_e32 v5, 0xffff0000, v5
	v_lshlrev_b32_e32 v22, 16, v6
	v_and_b32_e32 v6, 0xffff0000, v6
	v_lshlrev_b32_e32 v23, 16, v7
	v_and_b32_e32 v7, 0xffff0000, v7
	v_lshlrev_b32_e32 v24, 16, v8
	v_and_b32_e32 v8, 0xffff0000, v8
	v_lshlrev_b32_e32 v25, 16, v9
	v_and_b32_e32 v9, 0xffff0000, v9
	v_lshlrev_b32_e32 v26, 16, v10
	v_and_b32_e32 v10, 0xffff0000, v10
	v_lshlrev_b32_e32 v27, 16, v11
	v_and_b32_e32 v11, 0xffff0000, v11
	v_lshlrev_b32_e32 v28, 16, v12
	v_and_b32_e32 v12, 0xffff0000, v12
	v_lshlrev_b32_e32 v29, 16, v13
	v_and_b32_e32 v13, 0xffff0000, v13
	v_lshlrev_b32_e32 v30, 16, v14
	v_and_b32_e32 v14, 0xffff0000, v14
	v_lshlrev_b32_e32 v31, 16, v15
	v_and_b32_e32 v15, 0xffff0000, v15
	v_lshlrev_b32_e32 v32, 16, v16
	v_mul_f32_e32 v20, 0x3e38aa3b, v20
	v_cvt_pk_bf16_f32 v86, v20, v4
	v_mul_f32_e32 v2, 0x3e38aa3b, v2
	v_mul_f32_e32 v3, 0x3e38aa3b, v3
	v_and_b32_e32 v4, 0xffff0000, v17
	v_mul_f32_e32 v21, 0x3e38aa3b, v21
	v_mul_f32_e32 v5, 0x3e38aa3b, v5
	v_mul_f32_e32 v22, 0x3e38aa3b, v22
	v_mul_f32_e32 v6, 0x3e38aa3b, v6
	v_mul_f32_e32 v23, 0x3e38aa3b, v23
	v_mul_f32_e32 v7, 0x3e38aa3b, v7
	v_mul_f32_e32 v24, 0x3e38aa3b, v24
	v_mul_f32_e32 v8, 0x3e38aa3b, v8
	v_mul_f32_e32 v25, 0x3e38aa3b, v25
	v_mul_f32_e32 v9, 0x3e38aa3b, v9
	v_mul_f32_e32 v26, 0x3e38aa3b, v26
	v_mul_f32_e32 v10, 0x3e38aa3b, v10
	v_mul_f32_e32 v27, 0x3e38aa3b, v27
	v_mul_f32_e32 v11, 0x3e38aa3b, v11
	v_mul_f32_e32 v28, 0x3e38aa3b, v28
	v_mul_f32_e32 v12, 0x3e38aa3b, v12
	v_mul_f32_e32 v29, 0x3e38aa3b, v29
	v_mul_f32_e32 v13, 0x3e38aa3b, v13
	v_mul_f32_e32 v30, 0x3e38aa3b, v30
	v_mul_f32_e32 v14, 0x3e38aa3b, v14
	v_mul_f32_e32 v31, 0x3e38aa3b, v31
	v_mul_f32_e32 v15, 0x3e38aa3b, v15
	v_mul_f32_e32 v32, 0x3e38aa3b, v32
	v_cvt_pk_bf16_f32 v87, v21, v5
	v_cvt_pk_bf16_f32 v88, v22, v6
	v_cvt_pk_bf16_f32 v89, v23, v7
	v_cvt_pk_bf16_f32 v90, v24, v8
	v_cvt_pk_bf16_f32 v91, v25, v9
	v_cvt_pk_bf16_f32 v92, v26, v10
	v_cvt_pk_bf16_f32 v93, v27, v11
	v_cvt_pk_bf16_f32 v94, v28, v12
	v_cvt_pk_bf16_f32 v95, v29, v13
	v_mul_f32_e32 v4, 0x3e38aa3b, v4
	v_cvt_pk_bf16_f32 v96, v30, v14
	v_cvt_pk_bf16_f32 v97, v31, v15
	v_cvt_pk_bf16_f32 v98, v32, v2
	v_cvt_pk_bf16_f32 v99, v3, v4
	v_lshl_add_u64 v[2:3], s[8:9], 0, v[114:115]
	v_lshlrev_b64 v[2:3], 13, v[2:3]
	v_lshl_add_u64 v[4:5], vcc, 0, v[2:3]
	v_lshl_add_u64 v[2:3], s[74:75], 0, v[2:3]
	v_lshl_add_u64 v[2:3], v[2:3], 0, v[0:1]
	v_lshl_add_u64 v[4:5], v[4:5], 0, v[0:1]
	s_waitcnt vmcnt(0)
	s_waitcnt lgkmcnt(0)
	s_barrier
	s_cbranch_scc1 .LBB0_252
	s_cmp_lg_u32 s73, 1
	v_lshl_add_u64 v[124:125], vcc, 0, v[0:1]
	s_cselect_b64 vcc, -1, 0
	s_cmp_eq_u32 s73, 1
	v_lshl_add_u64 v[126:127], s[74:75], 0, v[0:1]
	s_cbranch_scc1 .LBB0_202
	s_ashr_i32 s41, s2, 9
	s_mulk_i32 s41, 0x2100
	s_add_i32 s41, s41, 192
	s_lshl_b32 s41, s41, 13
	s_and_b32 s40, s2, 15
	s_lshl_b32 s40, s40, 7
	s_add_u32 s38, s27, s40
	s_addc_u32 s39, s28, 0
	s_add_u32 s38, s38, s41
	s_addc_u32 s39, s39, 0
	s_add_i32 s40, s32, 0xc000
	s_mov_b32 m0, s40
	s_nop 0
	global_load_lds_dwordx4 v221, s[38:39]
	s_add_i32 m0, s40, 0x4000
	s_nop 0
	global_load_lds_dwordx4 v220, s[38:39]
.LBB0_202:
	v_add_u32_e32 v129, v136, v130
	ds_read_b128 v[2:5], v129 offset:16384
	ds_read_b128 v[18:21], v129 offset:20480
	v_add_u32_e32 v173, v136, v131
	ds_read_b128 v[34:37], v173 offset:16384
	ds_read_b128 v[38:41], v173 offset:20480
	v_add_u32_e32 v174, v136, v132
	s_waitcnt lgkmcnt(3)
	v_mfma_f32_32x32x16_bf16 v[2:17], v[2:5], v[84:87], 0
	v_add_u32_e32 v175, v136, v133
	s_waitcnt lgkmcnt(2)
	v_mfma_f32_32x32x16_bf16 v[18:33], v[18:21], v[84:87], 0
	s_waitcnt lgkmcnt(1)
	v_mfma_f32_32x32x16_bf16 v[2:17], v[34:37], v[88:91], v[2:17]
	s_waitcnt lgkmcnt(0)
	v_mfma_f32_32x32x16_bf16 v[18:33], v[38:41], v[88:91], v[18:33]
	ds_read_b128 v[34:37], v174 offset:16384
	ds_read_b128 v[38:41], v174 offset:20480
	s_waitcnt lgkmcnt(1)
	v_mfma_f32_32x32x16_bf16 v[2:17], v[34:37], v[92:95], v[2:17]
	s_waitcnt lgkmcnt(0)
	v_mfma_f32_32x32x16_bf16 v[18:33], v[38:41], v[92:95], v[18:33]
	ds_read_b128 v[34:37], v175 offset:16384
	ds_read_b128 v[38:41], v175 offset:20480
	s_waitcnt lgkmcnt(1)
	v_mfma_f32_32x32x16_bf16 v[2:17], v[34:37], v[96:99], v[2:17]
	s_waitcnt lgkmcnt(0)
	v_mfma_f32_32x32x16_bf16 v[18:33], v[38:41], v[96:99], v[18:33]
	s_nop 9
	v_max_f32_e32 v0, v3, v3
	v_max_f32_e32 v34, v2, v2
	v_max_f32_e32 v0, v34, v0
	v_max3_f32 v0, v0, v4, v5
	v_max3_f32 v0, v0, v6, v7
	v_max3_f32 v0, v0, v8, v9
	v_max3_f32 v0, v0, v10, v11
	v_max3_f32 v0, v0, v12, v13
	v_max3_f32 v0, v0, v14, v15
	v_max3_f32 v0, v0, v16, v17
	v_max3_f32 v0, v0, v18, v19
	v_max3_f32 v0, v0, v20, v21
	v_max3_f32 v0, v0, v22, v23
	v_max3_f32 v0, v0, v24, v25
	v_max3_f32 v0, v0, v26, v27
	v_max3_f32 v0, v0, v28, v29
	v_max3_f32 v0, v0, v30, v31
	v_max3_f32 v0, v0, v32, v33
	v_mov_b32_e32 v34, v0
	s_nop 1
	v_permlane32_swap_b32_e32 v0, v34
	v_max_f32_e32 v34, v34, v34
	v_max_f32_e32 v0, v0, v0
	v_max_f32_e32 v0, v0, v34
	v_sub_f32_e32 v2, v2, v0
	v_sub_f32_e32 v3, v3, v0
	v_exp_f32_e32 v2, v2
	v_sub_f32_e32 v4, v4, v0
	v_exp_f32_e32 v3, v3
	v_sub_f32_e32 v5, v5, v0
	v_exp_f32_e32 v4, v4
	v_sub_f32_e32 v18, v18, v0
	v_sub_f32_e32 v6, v6, v0
	v_exp_f32_e32 v5, v5
	v_sub_f32_e32 v7, v7, v0
	v_exp_f32_e32 v6, v6
	v_exp_f32_e32 v40, v18
	v_add_f32_e32 v18, 0, v2
	v_sub_f32_e32 v8, v8, v0
	v_exp_f32_e32 v7, v7
	v_add_f32_e32 v18, v3, v18
	v_sub_f32_e32 v9, v9, v0
	v_exp_f32_e32 v8, v8
	v_add_f32_e32 v18, v4, v18
	v_sub_f32_e32 v10, v10, v0
	v_exp_f32_e32 v9, v9
	v_add_f32_e32 v18, v5, v18
	v_sub_f32_e32 v11, v11, v0
	v_exp_f32_e32 v10, v10
	v_add_f32_e32 v18, v6, v18
	v_sub_f32_e32 v12, v12, v0
	v_exp_f32_e32 v11, v11
	v_add_f32_e32 v18, v7, v18
	v_sub_f32_e32 v13, v13, v0
	v_exp_f32_e32 v12, v12
	v_add_f32_e32 v18, v8, v18
	v_sub_f32_e32 v14, v14, v0
	v_exp_f32_e32 v13, v13
	v_add_f32_e32 v18, v9, v18
	v_sub_f32_e32 v15, v15, v0
	v_exp_f32_e32 v14, v14
	v_add_f32_e32 v18, v10, v18
	v_sub_f32_e32 v16, v16, v0
	v_exp_f32_e32 v15, v15
	v_add_f32_e32 v18, v11, v18
	v_sub_f32_e32 v17, v17, v0
	v_exp_f32_e32 v16, v16
	v_add_f32_e32 v18, v12, v18
	v_exp_f32_e32 v17, v17
	v_add_f32_e32 v18, v13, v18
	v_sub_f32_e32 v19, v19, v0
	v_add_f32_e32 v18, v14, v18
	v_sub_f32_e32 v20, v20, v0
	v_exp_f32_e32 v41, v19
	v_add_f32_e32 v18, v15, v18
	v_sub_f32_e32 v21, v21, v0
	v_exp_f32_e32 v42, v20
	v_add_f32_e32 v18, v16, v18
	v_sub_f32_e32 v22, v22, v0
	v_exp_f32_e32 v43, v21
	v_add_f32_e32 v18, v17, v18
	v_sub_f32_e32 v23, v23, v0
	v_exp_f32_e32 v22, v22
	v_add_f32_e32 v18, v40, v18
	v_sub_f32_e32 v24, v24, v0
	v_exp_f32_e32 v23, v23
	v_add_f32_e32 v18, v41, v18
	v_sub_f32_e32 v25, v25, v0
	v_exp_f32_e32 v24, v24
	v_add_f32_e32 v18, v42, v18
	v_sub_f32_e32 v26, v26, v0
	v_exp_f32_e32 v25, v25
	v_add_f32_e32 v18, v43, v18
	v_sub_f32_e32 v27, v27, v0
	v_exp_f32_e32 v26, v26
	v_add_f32_e32 v18, v22, v18
	v_sub_f32_e32 v28, v28, v0
	v_exp_f32_e32 v27, v27
	v_add_f32_e32 v18, v23, v18
	v_sub_f32_e32 v29, v29, v0
	v_exp_f32_e32 v28, v28
	v_add_f32_e32 v18, v24, v18
	v_sub_f32_e32 v30, v30, v0
	v_exp_f32_e32 v29, v29
	v_add_f32_e32 v18, v25, v18
	v_sub_f32_e32 v31, v31, v0
	v_exp_f32_e32 v30, v30
	v_add_f32_e32 v18, v26, v18
	v_sub_f32_e32 v32, v32, v0
	v_exp_f32_e32 v31, v31
	v_add_f32_e32 v18, v27, v18
	v_sub_f32_e32 v33, v33, v0
	v_exp_f32_e32 v32, v32
	v_add_f32_e32 v18, v28, v18
	v_exp_f32_e32 v33, v33
	v_add_f32_e32 v18, v29, v18
	v_add_f32_e32 v18, v30, v18
	v_add_f32_e32 v18, v31, v18
	v_add_f32_e32 v18, v32, v18
	v_add_f32_e32 v34, v33, v18
	v_mov_b32_e32 v35, v34
	s_nop 1
	v_permlane32_swap_b32_e32 v34, v35
	v_cvt_pk_bf16_f32 v18, v2, v3
	v_cvt_pk_bf16_f32 v19, v4, v5
	v_cvt_pk_bf16_f32 v20, v6, v7
	v_cvt_pk_bf16_f32 v21, v8, v9
	v_cvt_pk_bf16_f32 v36, v10, v11
	v_cvt_pk_bf16_f32 v37, v12, v13
	v_cvt_pk_bf16_f32 v38, v14, v15
	v_cvt_pk_bf16_f32 v39, v16, v17
	v_cvt_pk_bf16_f32 v40, v40, v41
	v_cvt_pk_bf16_f32 v41, v42, v43
	v_cvt_pk_bf16_f32 v42, v22, v23
	v_cvt_pk_bf16_f32 v43, v24, v25
	v_cvt_pk_bf16_f32 v44, v26, v27
	v_cvt_pk_bf16_f32 v45, v28, v29
	v_cvt_pk_bf16_f32 v46, v30, v31
	v_cvt_pk_bf16_f32 v47, v32, v33
	ds_read_b64_tr_b16 v[2:3], v135 offset:0
	ds_read_b64_tr_b16 v[4:5], v135 offset:0x400
	ds_read_b64_tr_b16 v[22:23], v135 offset:0x800
	ds_read_b64_tr_b16 v[24:25], v135 offset:0xc00
	ds_read_b64_tr_b16 v[26:27], v135 offset:0x1000
	ds_read_b64_tr_b16 v[28:29], v135 offset:0x1400
	ds_read_b64_tr_b16 v[30:31], v135 offset:0x1800
	ds_read_b64_tr_b16 v[32:33], v135 offset:0x1c00
	s_waitcnt lgkmcnt(0)
	s_nop 0
	v_mfma_f32_32x32x16_bf16 v[2:17], v[18:21], v[2:5], 0
	v_mfma_f32_32x32x16_bf16 v[2:17], v[36:39], v[22:25], v[2:17]
	ds_read_b64_tr_b16 v[22:23], v135 offset:0x200
	ds_read_b64_tr_b16 v[24:25], v135 offset:0x600
	ds_read_b64_tr_b16 v[48:49], v135 offset:0xa00
	ds_read_b64_tr_b16 v[50:51], v135 offset:0xe00
	ds_read_b64_tr_b16 v[52:53], v135 offset:0x1200
	ds_read_b64_tr_b16 v[54:55], v135 offset:0x1600
	ds_read_b64_tr_b16 v[56:57], v135 offset:0x1a00
	v_mfma_f32_32x32x16_bf16 v[2:17], v[40:43], v[26:29], v[2:17]
	ds_read_b64_tr_b16 v[58:59], v135 offset:0x1e00
	s_waitcnt lgkmcnt(0)
	v_mfma_f32_32x32x16_bf16 v[2:17], v[44:47], v[30:33], v[2:17]
	v_mfma_f32_32x32x16_bf16 v[18:33], v[18:21], v[22:25], 0
	v_mfma_f32_32x32x16_bf16 v[18:33], v[36:39], v[48:51], v[18:33]
	v_cndmask_b32_e64 v36, 0, 1, vcc
	v_cmp_ne_u32_e64 s[74:75], 1, v36
	s_andn2_b64 vcc, exec, vcc
	v_mfma_f32_32x32x16_bf16 v[18:33], v[40:43], v[52:55], v[18:33]
	v_mfma_f32_32x32x16_bf16 v[18:33], v[44:47], v[56:59], v[18:33]
	s_cbranch_vccnz .LBB0_204
	s_waitcnt vmcnt(2)
.LBB0_204:
	v_add_f32_e32 v34, v34, v35
	v_add_f32_e32 v128, 0, v34
	s_and_b64 vcc, exec, s[74:75]
	s_waitcnt lgkmcnt(0)
	s_barrier
	s_cbranch_vccnz .LBB0_256
	s_cmp_gt_u32 s73, 2
	s_cselect_b64 s[74:75], -1, 0
	s_cmp_lt_u32 s73, 3
	s_cbranch_scc1 .LBB0_207
	s_add_i32 s41, s24, -4
	s_max_i32 s41, s41, 0
	s_min_i32 s41, s41, 0x7f
	s_lshl_b32 s41, s41, 6
	s_add_i32 s41, s41, s25
	s_lshl_b32 s41, s41, 13
	s_and_b32 s40, s2, 15
	s_lshl_b32 s40, s40, 7
	s_add_u32 s38, s27, s40
	s_addc_u32 s39, s28, 0
	s_add_u32 s38, s38, s41
	s_addc_u32 s39, s39, 0
	s_add_i32 s40, s32, 0x0
	s_mov_b32 m0, s40
	s_nop 0
	global_load_lds_dwordx4 v221, s[38:39]
	s_add_i32 m0, s40, 0x4000
	s_nop 0
	global_load_lds_dwordx4 v220, s[38:39]

.LBB0_213:
	ds_read_b64_tr_b16 v[54:55], v139 offset:0
	ds_read_b64_tr_b16 v[56:57], v139 offset:0x400
	ds_read_b64_tr_b16 v[58:59], v139 offset:0x800
	ds_read_b64_tr_b16 v[60:61], v139 offset:0xc00
	ds_read_b64_tr_b16 v[62:63], v139 offset:0x1000
	ds_read_b64_tr_b16 v[64:65], v139 offset:0x1400
	ds_read_b64_tr_b16 v[66:67], v139 offset:0x1800
	ds_read_b64_tr_b16 v[68:69], v139 offset:0x1c00
	s_nop 0
	s_waitcnt lgkmcnt(6)
	v_mfma_f32_32x32x16_bf16 v[2:17], v[50:53], v[54:57], v[2:17]
	ds_read_b64_tr_b16 v[54:55], v139 offset:0x200
	ds_read_b64_tr_b16 v[56:57], v139 offset:0x600
	s_waitcnt lgkmcnt(6)
	v_mfma_f32_32x32x16_bf16 v[2:17], v[46:49], v[58:61], v[2:17]
	ds_read_b64_tr_b16 v[58:59], v139 offset:0xa00
	ds_read_b64_tr_b16 v[60:61], v139 offset:0xe00
	s_waitcnt lgkmcnt(6)
	v_mfma_f32_32x32x16_bf16 v[2:17], v[42:45], v[62:65], v[2:17]
	ds_read_b64_tr_b16 v[62:63], v139 offset:0x1200
	ds_read_b64_tr_b16 v[64:65], v139 offset:0x1600
	s_waitcnt lgkmcnt(6)
	v_mfma_f32_32x32x16_bf16 v[2:17], v[38:41], v[66:69], v[2:17]
	ds_read_b64_tr_b16 v[66:67], v139 offset:0x1a00
	ds_read_b64_tr_b16 v[68:69], v139 offset:0x1e00
	s_waitcnt lgkmcnt(6)
	v_mfma_f32_32x32x16_bf16 v[18:33], v[50:53], v[54:57], v[18:33]
	s_andn2_b64 vcc, exec, s[74:75]
	s_waitcnt lgkmcnt(4)
	v_mfma_f32_32x32x16_bf16 v[18:33], v[46:49], v[58:61], v[18:33]
	s_waitcnt lgkmcnt(2)
	v_mfma_f32_32x32x16_bf16 v[18:33], v[42:45], v[62:65], v[18:33]
	s_waitcnt lgkmcnt(0)
	v_mfma_f32_32x32x16_bf16 v[18:33], v[38:41], v[66:69], v[18:33]
	s_cbranch_vccnz .LBB0_215
	s_waitcnt vmcnt(4)
.LBB0_215:
	v_add_f32_e32 v35, v35, v37
	v_fmac_f32_e32 v35, v128, v176
	s_cmp_eq_u32 s73, 2
	s_waitcnt lgkmcnt(0)
	s_barrier
	s_cbranch_scc1 .LBB0_255
	s_cmp_gt_u32 s73, 3
	s_cselect_b64 s[74:75], -1, 0
	s_cmp_lt_u32 s73, 4
	s_cbranch_scc1 .LBB0_218
	s_add_i32 s41, s24, -3
	s_max_i32 s41, s41, 0
	s_min_i32 s41, s41, 0x7f
	s_lshl_b32 s41, s41, 6
	s_add_i32 s41, s41, s25
	s_lshl_b32 s41, s41, 13
	s_and_b32 s40, s2, 15
	s_lshl_b32 s40, s40, 7
	s_add_u32 s38, s27, s40
	s_addc_u32 s39, s28, 0
	s_add_u32 s38, s38, s41
	s_addc_u32 s39, s39, 0
	s_add_i32 s40, s32, 0x2000
	s_mov_b32 m0, s40
	s_nop 0
	global_load_lds_dwordx4 v221, s[38:39]
	s_add_i32 m0, s40, 0x4000
	s_nop 0
	global_load_lds_dwordx4 v220, s[38:39]
.LBB0_218:
	v_mov_b32_e32 v37, v34
	v_mov_b32_e32 v38, v34
	v_mov_b32_e32 v39, v34
	v_mov_b32_e32 v40, v34
	v_mov_b32_e32 v41, v34
	v_mov_b32_e32 v42, v34
	v_mov_b32_e32 v43, v34
	v_mov_b32_e32 v44, v34
	v_mov_b32_e32 v45, v34
	v_mov_b32_e32 v46, v34
	v_mov_b32_e32 v47, v34
	v_mov_b32_e32 v48, v34
	v_mov_b32_e32 v49, v34
	v_mov_b32_e32 v50, v34
	v_mov_b32_e32 v51, v34
	ds_read_b128 v[52:55], v222 offset:16384
	ds_read_b128 v[180:183], v222 offset:20480
	s_waitcnt lgkmcnt(1)
	v_mfma_f32_32x32x16_bf16 v[68:83], v[52:55], v[84:87], v[36:51]
	s_waitcnt lgkmcnt(0)
	v_mfma_f32_32x32x16_bf16 v[52:67], v[180:183], v[84:87], v[36:51]
	ds_read_b128 v[180:183], v223 offset:16384
	ds_read_b128 v[184:187], v223 offset:20480
	s_waitcnt lgkmcnt(1)
	v_mfma_f32_32x32x16_bf16 v[68:83], v[180:183], v[88:91], v[68:83]
	s_waitcnt lgkmcnt(0)
	v_mfma_f32_32x32x16_bf16 v[52:67], v[184:187], v[88:91], v[52:67]
	ds_read_b128 v[180:183], v224 offset:16384
	ds_read_b128 v[184:187], v224 offset:20480
	s_waitcnt lgkmcnt(1)
	v_mfma_f32_32x32x16_bf16 v[68:83], v[180:183], v[92:95], v[68:83]
	s_waitcnt lgkmcnt(0)
	v_mfma_f32_32x32x16_bf16 v[52:67], v[184:187], v[92:95], v[52:67]
	ds_read_b128 v[180:183], v225 offset:16384
	ds_read_b128 v[184:187], v225 offset:20480
	s_waitcnt lgkmcnt(1)
	v_mfma_f32_32x32x16_bf16 v[68:83], v[180:183], v[96:99], v[68:83]
	s_waitcnt lgkmcnt(0)
	v_mfma_f32_32x32x16_bf16 v[52:67], v[184:187], v[96:99], v[52:67]
	s_nop 9
	v_max_f32_e32 v128, v69, v69
	v_max_f32_e32 v176, v68, v68
	v_max_f32_e32 v128, v176, v128
	v_max3_f32 v128, v128, v70, v71
	v_max3_f32 v128, v128, v72, v73
	v_max3_f32 v128, v128, v74, v75
	v_max3_f32 v128, v128, v76, v77
	v_max3_f32 v128, v128, v78, v79
	v_max3_f32 v128, v128, v80, v81
	v_max3_f32 v128, v128, v82, v83
	v_max3_f32 v128, v128, v52, v53
	v_max3_f32 v128, v128, v54, v55
	v_max3_f32 v128, v128, v56, v57
	v_max3_f32 v128, v128, v58, v59
	v_max3_f32 v128, v128, v60, v61
	v_max3_f32 v128, v128, v62, v63
	v_max3_f32 v128, v128, v64, v65
	v_max3_f32 v128, v128, v66, v67
	v_mov_b32_e32 v176, v128
	s_nop 1
	v_permlane32_swap_b32_e32 v128, v176
	v_max_f32_e32 v176, v176, v176
	v_max_f32_e32 v128, v128, v128
	v_max_f32_e32 v176, v128, v176
	v_cmp_ge_f32_e32 vcc, s64, v176
	s_cmp_eq_u64 vcc, exec
	v_mov_b32_e32 v128, 1.0
	s_cbranch_scc0 .LBB0_264

.LBB0_223:
	ds_read_b64_tr_b16 v[70:71], v226 offset:0
	ds_read_b64_tr_b16 v[72:73], v226 offset:0x400
	ds_read_b64_tr_b16 v[74:75], v226 offset:0x800
	ds_read_b64_tr_b16 v[76:77], v226 offset:0xc00
	ds_read_b64_tr_b16 v[78:79], v226 offset:0x1000
	ds_read_b64_tr_b16 v[80:81], v226 offset:0x1400
	ds_read_b64_tr_b16 v[180:181], v226 offset:0x1800
	ds_read_b64_tr_b16 v[182:183], v226 offset:0x1c00
	s_nop 0
	s_waitcnt lgkmcnt(6)
	v_mfma_f32_32x32x16_bf16 v[2:17], v[64:67], v[70:73], v[2:17]
	ds_read_b64_tr_b16 v[70:71], v226 offset:0x200
	ds_read_b64_tr_b16 v[72:73], v226 offset:0x600
	s_waitcnt lgkmcnt(6)
	v_mfma_f32_32x32x16_bf16 v[2:17], v[60:63], v[74:77], v[2:17]
	ds_read_b64_tr_b16 v[74:75], v226 offset:0xa00
	ds_read_b64_tr_b16 v[76:77], v226 offset:0xe00
	s_waitcnt lgkmcnt(6)
	v_mfma_f32_32x32x16_bf16 v[2:17], v[56:59], v[78:81], v[2:17]
	ds_read_b64_tr_b16 v[78:79], v226 offset:0x1200
	ds_read_b64_tr_b16 v[80:81], v226 offset:0x1600
	s_waitcnt lgkmcnt(6)
	v_mfma_f32_32x32x16_bf16 v[2:17], v[52:55], v[180:183], v[2:17]
	ds_read_b64_tr_b16 v[180:181], v226 offset:0x1a00
	ds_read_b64_tr_b16 v[182:183], v226 offset:0x1e00
	s_waitcnt lgkmcnt(6)
	v_mfma_f32_32x32x16_bf16 v[18:33], v[64:67], v[70:73], v[18:33]
	s_andn2_b64 vcc, exec, s[74:75]
	s_waitcnt lgkmcnt(4)
	v_mfma_f32_32x32x16_bf16 v[18:33], v[60:63], v[74:77], v[18:33]
	s_waitcnt lgkmcnt(2)
	v_mfma_f32_32x32x16_bf16 v[18:33], v[56:59], v[78:81], v[18:33]
	s_waitcnt lgkmcnt(0)
	v_mfma_f32_32x32x16_bf16 v[18:33], v[52:55], v[180:183], v[18:33]
	s_cbranch_vccnz .LBB0_225
	s_waitcnt vmcnt(4)
.LBB0_225:
	v_add_f32_e32 v68, v68, v69
	v_fmac_f32_e32 v68, v35, v128
	s_cmp_eq_u32 s73, 3
	s_waitcnt lgkmcnt(0)
	s_barrier
	s_cbranch_scc1 .LBB0_254
	s_cmp_gt_u32 s73, 4
	s_cselect_b64 s[8:9], -1, 0
	s_cmp_lt_u32 s73, 5
	s_cbranch_scc1 .LBB0_228
	s_add_i32 s41, s24, -2
	s_max_i32 s41, s41, 0
	s_min_i32 s41, s41, 0x7f
	s_lshl_b32 s41, s41, 6
	s_add_i32 s41, s41, s25
	s_lshl_b32 s41, s41, 13
	s_and_b32 s40, s2, 15
	s_lshl_b32 s40, s40, 7
	s_add_u32 s38, s27, s40
	s_addc_u32 s39, s28, 0
	s_add_u32 s38, s38, s41
	s_addc_u32 s39, s39, 0
	s_add_i32 s40, s32, 0xa000
	s_mov_b32 m0, s40
	s_nop 0
	global_load_lds_dwordx4 v221, s[38:39]
	s_add_i32 m0, s40, 0x4000
	s_nop 0
	global_load_lds_dwordx4 v220, s[38:39]
.LBB0_228:
	ds_read_b128 v[70:73], v222 offset:24576
	ds_read_b128 v[74:77], v222 offset:28672
	s_waitcnt lgkmcnt(1)
	v_mfma_f32_32x32x16_bf16 v[52:67], v[70:73], v[84:87], v[36:51]
	s_waitcnt lgkmcnt(0)
	v_mfma_f32_32x32x16_bf16 v[36:51], v[74:77], v[84:87], v[36:51]
	ds_read_b128 v[70:73], v223 offset:24576
	ds_read_b128 v[74:77], v223 offset:28672
	s_waitcnt lgkmcnt(1)
	v_mfma_f32_32x32x16_bf16 v[52:67], v[70:73], v[88:91], v[52:67]
	s_waitcnt lgkmcnt(0)
	v_mfma_f32_32x32x16_bf16 v[36:51], v[74:77], v[88:91], v[36:51]
	ds_read_b128 v[70:73], v224 offset:24576
	ds_read_b128 v[74:77], v224 offset:28672
	s_waitcnt lgkmcnt(1)
	v_mfma_f32_32x32x16_bf16 v[52:67], v[70:73], v[92:95], v[52:67]
	s_waitcnt lgkmcnt(0)
	v_mfma_f32_32x32x16_bf16 v[36:51], v[74:77], v[92:95], v[36:51]
	ds_read_b128 v[70:73], v225 offset:24576
	ds_read_b128 v[74:77], v225 offset:28672
	s_waitcnt lgkmcnt(1)
	v_mfma_f32_32x32x16_bf16 v[52:67], v[70:73], v[96:99], v[52:67]
	s_waitcnt lgkmcnt(0)
	v_mfma_f32_32x32x16_bf16 v[36:51], v[74:77], v[96:99], v[36:51]
	s_nop 9
	v_max_f32_e32 v35, v53, v53
	v_max_f32_e32 v69, v52, v52
	v_max_f32_e32 v35, v69, v35
	v_max3_f32 v35, v35, v54, v55
	v_max3_f32 v35, v35, v56, v57
	v_max3_f32 v35, v35, v58, v59
	v_max3_f32 v35, v35, v60, v61
	v_max3_f32 v35, v35, v62, v63
	v_max3_f32 v35, v35, v64, v65
	v_max3_f32 v35, v35, v66, v67
	v_max3_f32 v35, v35, v36, v37
	v_max3_f32 v35, v35, v38, v39
	v_max3_f32 v35, v35, v40, v41
	v_max3_f32 v35, v35, v42, v43
	v_max3_f32 v35, v35, v44, v45
	v_max3_f32 v35, v35, v46, v47
	v_max3_f32 v35, v35, v48, v49
	v_max3_f32 v35, v35, v50, v51
	v_mov_b32_e32 v69, v35
	s_nop 1
	v_permlane32_swap_b32_e32 v35, v69
	v_max_f32_e32 v69, v69, v69
	v_max_f32_e32 v35, v35, v35
	v_max_f32_e32 v69, v35, v69
	v_cmp_ge_f32_e32 vcc, s64, v69
	s_cmp_eq_u64 vcc, exec
	v_mov_b32_e32 v35, 1.0
	s_cbranch_scc0 .LBB0_265

.LBB0_233:
	ds_read_b64_tr_b16 v[54:55], v227 offset:0
	ds_read_b64_tr_b16 v[56:57], v227 offset:0x400
	ds_read_b64_tr_b16 v[58:59], v227 offset:0x800
	ds_read_b64_tr_b16 v[60:61], v227 offset:0xc00
	ds_read_b64_tr_b16 v[62:63], v227 offset:0x1000
	ds_read_b64_tr_b16 v[64:65], v227 offset:0x1400
	ds_read_b64_tr_b16 v[70:71], v227 offset:0x1800
	ds_read_b64_tr_b16 v[72:73], v227 offset:0x1c00
	s_nop 0
	s_waitcnt lgkmcnt(6)
	v_mfma_f32_32x32x16_bf16 v[2:17], v[48:51], v[54:57], v[2:17]
	ds_read_b64_tr_b16 v[54:55], v227 offset:0x200
	ds_read_b64_tr_b16 v[56:57], v227 offset:0x600
	s_waitcnt lgkmcnt(6)
	v_mfma_f32_32x32x16_bf16 v[2:17], v[44:47], v[58:61], v[2:17]
	ds_read_b64_tr_b16 v[58:59], v227 offset:0xa00
	ds_read_b64_tr_b16 v[60:61], v227 offset:0xe00
	s_waitcnt lgkmcnt(6)
	v_mfma_f32_32x32x16_bf16 v[2:17], v[40:43], v[62:65], v[2:17]
	ds_read_b64_tr_b16 v[62:63], v227 offset:0x1200
	ds_read_b64_tr_b16 v[64:65], v227 offset:0x1600
	s_waitcnt lgkmcnt(6)
	v_mfma_f32_32x32x16_bf16 v[2:17], v[36:39], v[70:73], v[2:17]
	ds_read_b64_tr_b16 v[70:71], v227 offset:0x1a00
	ds_read_b64_tr_b16 v[72:73], v227 offset:0x1e00
	s_waitcnt lgkmcnt(6)
	v_mfma_f32_32x32x16_bf16 v[18:33], v[48:51], v[54:57], v[18:33]
	s_andn2_b64 vcc, exec, s[8:9]
	s_waitcnt lgkmcnt(4)
	v_mfma_f32_32x32x16_bf16 v[18:33], v[44:47], v[58:61], v[18:33]
	s_waitcnt lgkmcnt(2)
	v_mfma_f32_32x32x16_bf16 v[18:33], v[40:43], v[62:65], v[18:33]
	s_waitcnt lgkmcnt(0)
	v_mfma_f32_32x32x16_bf16 v[18:33], v[36:39], v[70:73], v[18:33]
	s_cbranch_vccnz .LBB0_235
	s_waitcnt vmcnt(4)

.LBB0_238:
	s_cmp_gt_u32 s39, 8
	s_cbranch_scc1 .Lna_nodma
	s_add_i32 s8, s39, 3
	s_add_i32 s41, s24, s8
	s_add_i32 s41, s41, -4
	s_max_i32 s41, s41, 0
	s_min_i32 s41, s41, 0x7f
	s_lshl_b32 s41, s41, 6
	s_add_i32 s41, s41, s25
	s_lshl_b32 s41, s41, 13
	s_and_b32 s40, s2, 15
	s_lshl_b32 s40, s40, 7
	s_add_u32 s74, s27, s40
	s_addc_u32 s75, s28, 0
	s_add_u32 s74, s74, s41
	s_addc_u32 s75, s75, 0
	s_and_b32 s40, s8, 3
	s_lshl_b32 s40, s40, 2
	s_lshr_b32 s40, 0x6510, s40
	s_and_b32 s40, s40, 15
	s_lshl_b32 s40, s40, 13
	s_add_i32 s40, s40, s32
	s_mov_b32 m0, s40
	s_nop 0
	global_load_lds_dwordx4 v221, s[74:75]
	s_add_i32 m0, s40, 0x4000
	s_nop 0
	global_load_lds_dwordx4 v220, s[74:75]
.Lna_nodma:
	s_cmp_eq_u32 s39, 11
	s_cbranch_scc0 .Lna_nogate
	s_lshl_b32 s8, s92, 7
	s_add_u32 s8, s34, s8
	s_addc_u32 s9, s35, 0
	s_add_u32 s8, s8, 0x1800
	s_addc_u32 s9, s9, 0
	v_lshl_add_u32 v188, v108, 1, v120
	v_add_u32_e32 v188, v188, v122
	global_load_ushort v228, v188, s[8:9] offset:0
	global_load_ushort v229, v188, s[8:9] offset:64
	s_add_u32 s8, s8, 0x2000
	s_addc_u32 s9, s9, 0
	global_load_ushort v230, v188, s[8:9] offset:0
	global_load_ushort v231, v188, s[8:9] offset:64
	s_add_u32 s8, s8, 0x2000
	s_addc_u32 s9, s9, 0
	global_load_ushort v232, v188, s[8:9] offset:0
	global_load_ushort v233, v188, s[8:9] offset:64
	s_add_u32 s8, s8, 0x2000
	s_addc_u32 s9, s9, 0
	global_load_ushort v234, v188, s[8:9] offset:0
	global_load_ushort v235, v188, s[8:9] offset:64
	s_add_u32 s8, s8, 0xa000
	s_addc_u32 s9, s9, 0
	global_load_ushort v236, v188, s[8:9] offset:0
	global_load_ushort v237, v188, s[8:9] offset:64
	s_add_u32 s8, s8, 0x2000
	s_addc_u32 s9, s9, 0
	global_load_ushort v238, v188, s[8:9] offset:0
	global_load_ushort v239, v188, s[8:9] offset:64
	s_add_u32 s8, s8, 0x2000
	s_addc_u32 s9, s9, 0
	global_load_ushort v240, v188, s[8:9] offset:0
	global_load_ushort v241, v188, s[8:9] offset:64
	s_add_u32 s8, s8, 0x2000
	s_addc_u32 s9, s9, 0
	global_load_ushort v242, v188, s[8:9] offset:0
	global_load_ushort v243, v188, s[8:9] offset:64
	s_add_u32 s8, s8, 0xa000
	s_addc_u32 s9, s9, 0
	global_load_ushort v244, v188, s[8:9] offset:0
	global_load_ushort v245, v188, s[8:9] offset:64
	s_add_u32 s8, s8, 0x2000
	s_addc_u32 s9, s9, 0
	global_load_ushort v246, v188, s[8:9] offset:0
	global_load_ushort v247, v188, s[8:9] offset:64
	s_add_u32 s8, s8, 0x2000
	s_addc_u32 s9, s9, 0
	global_load_ushort v248, v188, s[8:9] offset:0
	global_load_ushort v249, v188, s[8:9] offset:64
	s_add_u32 s8, s8, 0x2000
	s_addc_u32 s9, s9, 0
	global_load_ushort v250, v188, s[8:9] offset:0
	global_load_ushort v251, v188, s[8:9] offset:64
	s_add_u32 s8, s8, 0xa000
	s_addc_u32 s9, s9, 0
	global_load_ushort v252, v188, s[8:9] offset:0
	global_load_ushort v253, v188, s[8:9] offset:64
	s_add_u32 s8, s8, 0x2000
	s_addc_u32 s9, s9, 0
	global_load_ushort v189, v188, s[8:9] offset:0
	global_load_ushort v190, v188, s[8:9] offset:64
	s_add_u32 s8, s8, 0x2000
	s_addc_u32 s9, s9, 0
	global_load_ushort v191, v188, s[8:9] offset:0
	global_load_ushort v192, v188, s[8:9] offset:64
	s_add_u32 s8, s8, 0x2000
	s_addc_u32 s9, s9, 0
	global_load_ushort v193, v188, s[8:9] offset:0
	global_load_ushort v194, v188, s[8:9] offset:64

.LBB0_242:
	s_add_i32 s40, s39, 4
	s_and_b32 s40, s40, 1
	s_add_i32 s41, s41, -4
	v_cmp_ge_i32_e32 vcc, s41, v173
	v_cmp_lt_i32_e64 s[74:75], s41, v174
	s_and_b64 vcc, vcc, s[74:75]
	s_and_saveexec_b64 s[74:75], vcc
	s_cbranch_execz .LBB0_249
	s_and_b32 s41, s39, 3
	s_lshl_b32 s41, s41, 2
	s_lshr_b32 s41, 0x6510, s41
	s_and_b32 s41, s41, 15
	s_lshl_b32 s41, s41, 13
	v_add_u32_e32 v82, s41, v136
	v_add_u32_e32 v50, v82, v130
	ds_read_b128 v[66:69], v50 offset:16384
	ds_read_b128 v[180:183], v50 offset:20480
	v_add_u32_e32 v83, v82, v131
	v_add_u32_e32 v128, v175, v169
	v_readlane_b32 vcc_lo, v254, 22
	s_waitcnt lgkmcnt(1)
	v_mfma_f32_32x32x16_bf16 v[50:65], v[66:69], v[84:87], v[34:49]
	v_readlane_b32 vcc_hi, v254, 23
	s_waitcnt lgkmcnt(0)
	v_mfma_f32_32x32x16_bf16 v[66:81], v[180:183], v[84:87], v[34:49]
	ds_read_b128 v[180:183], v83 offset:16384
	ds_read_b128 v[184:187], v83 offset:20480
	v_add_u32_e32 v83, v82, v132
	v_add_u32_e32 v82, v82, v133
	s_waitcnt lgkmcnt(0)
	v_mfma_f32_32x32x16_bf16 v[66:81], v[184:187], v[88:91], v[66:81]
	v_mfma_f32_32x32x16_bf16 v[50:65], v[180:183], v[88:91], v[50:65]
	ds_read_b128 v[180:183], v83 offset:16384
	ds_read_b128 v[184:187], v83 offset:20480
	v_add_u32_e32 v83, v175, v171
	s_waitcnt lgkmcnt(0)
	v_mfma_f32_32x32x16_bf16 v[66:81], v[184:187], v[92:95], v[66:81]
	v_mfma_f32_32x32x16_bf16 v[50:65], v[180:183], v[92:95], v[50:65]
	ds_read_b128 v[180:183], v82 offset:16384
	ds_read_b128 v[184:187], v82 offset:20480
	v_add_u32_e32 v82, v175, v172
	ds_read_b32 v82, v82 offset:35260
	ds_read_b32 v83, v83 offset:35260
	ds_read_b32 v128, v128 offset:35260
	s_waitcnt lgkmcnt(3)
	v_mfma_f32_32x32x16_bf16 v[66:81], v[184:187], v[96:99], v[66:81]
	v_mfma_f32_32x32x16_bf16 v[50:65], v[180:183], v[96:99], v[50:65]
	s_waitcnt lgkmcnt(1)
	s_nop 9
	v_add_f32_e32 v66, v66, v83
	v_add_u32_e32 v83, v175, v170
	ds_read_b32 v83, v83 offset:35260
	v_cndmask_b32_e32 v66, v218, v66, vcc
	v_readlane_b32 vcc_lo, v254, 26
	v_readlane_b32 vcc_hi, v254, 27
	s_waitcnt lgkmcnt(0)
	v_pk_add_f32 v[82:83], v[50:51], v[82:83]
	s_nop 0
	v_cndmask_b32_e32 v51, v82, v218, vcc
	v_readlane_b32 vcc_lo, v254, 24
	v_readlane_b32 vcc_hi, v254, 25
	v_add_f32_e32 v50, v67, v128
	s_nop 0
	v_cndmask_b32_e32 v82, v83, v218, vcc
	v_readlane_b32 vcc_lo, v254, 28
	v_readlane_b32 vcc_hi, v254, 29
	s_nop 1
	v_cndmask_b32_e32 v67, v218, v50, vcc
	v_add_u32_e32 v50, v175, v168
	ds_read_b32 v128, v50 offset:35260
	v_add_u32_e32 v50, v175, v167
	ds_read_b32 v50, v50 offset:35260
	v_readlane_b32 vcc_lo, v254, 30
	v_readlane_b32 vcc_hi, v254, 31
	s_waitcnt lgkmcnt(0)
	v_add_f32_e32 v50, v68, v50
	v_cndmask_b32_e32 v68, v218, v50, vcc
	v_add_u32_e32 v50, v175, v166
	ds_read_b32 v129, v50 offset:35260
	v_add_u32_e32 v50, v175, v165
	ds_read_b32 v50, v50 offset:35260
	v_readlane_b32 vcc_lo, v254, 34
	v_readlane_b32 vcc_hi, v254, 35
	s_waitcnt lgkmcnt(1)
	v_pk_add_f32 v[52:53], v[52:53], v[128:129]
	s_waitcnt lgkmcnt(0)
	v_add_f32_e32 v50, v69, v50
	v_cndmask_b32_e32 v83, v52, v218, vcc
	v_readlane_b32 vcc_lo, v254, 32
	v_readlane_b32 vcc_hi, v254, 33
	s_nop 1
	v_cndmask_b32_e32 v128, v53, v218, vcc
	v_readlane_b32 vcc_lo, v254, 36
	v_readlane_b32 vcc_hi, v254, 37
	s_nop 1
	v_cndmask_b32_e32 v69, v218, v50, vcc
	v_add_u32_e32 v50, v175, v164
	ds_read_b32 v180, v50 offset:35260
	v_add_u32_e32 v50, v175, v163
	ds_read_b32 v50, v50 offset:35260
	v_readlane_b32 vcc_lo, v254, 38
	v_readlane_b32 vcc_hi, v254, 39
	s_waitcnt lgkmcnt(0)
	v_add_f32_e32 v50, v70, v50
	v_cndmask_b32_e32 v52, v218, v50, vcc
	v_add_u32_e32 v50, v175, v162
	ds_read_b32 v181, v50 offset:35260
	v_add_u32_e32 v50, v175, v161
	ds_read_b32 v50, v50 offset:35260
	v_readlane_b32 vcc_lo, v254, 42
	v_readlane_b32 vcc_hi, v254, 43
	s_waitcnt lgkmcnt(1)
	v_pk_add_f32 v[54:55], v[54:55], v[180:181]
	s_waitcnt lgkmcnt(0)
	v_add_f32_e32 v50, v71, v50
	v_cndmask_b32_e32 v129, v54, v218, vcc
	v_readlane_b32 vcc_lo, v254, 40
	v_readlane_b32 vcc_hi, v254, 41
	s_nop 1
	v_cndmask_b32_e32 v54, v55, v218, vcc
	v_readlane_b32 vcc_lo, v254, 44
	v_readlane_b32 vcc_hi, v254, 45
	s_nop 1
	v_cndmask_b32_e32 v53, v218, v50, vcc
	v_add_u32_e32 v50, v175, v160
	ds_read_b32 v180, v50 offset:35260
	v_add_u32_e32 v50, v175, v159
	ds_read_b32 v50, v50 offset:35260
	v_readlane_b32 vcc_lo, v254, 46
	v_readlane_b32 vcc_hi, v254, 47
	s_waitcnt lgkmcnt(0)
	v_add_f32_e32 v50, v72, v50
	v_cndmask_b32_e32 v70, v218, v50, vcc
	v_add_u32_e32 v50, v175, v158
	ds_read_b32 v181, v50 offset:35260
	v_add_u32_e32 v50, v175, v157
	ds_read_b32 v50, v50 offset:35260
	v_readlane_b32 vcc_lo, v254, 50
	v_readlane_b32 vcc_hi, v254, 51
	s_waitcnt lgkmcnt(1)
	v_pk_add_f32 v[56:57], v[56:57], v[180:181]
	s_nop 0
	v_cndmask_b32_e32 v55, v56, v218, vcc
	v_readlane_b32 vcc_lo, v254, 48
	v_readlane_b32 vcc_hi, v254, 49
	s_nop 1
	v_cndmask_b32_e32 v56, v57, v218, vcc
	v_readlane_b32 vcc_lo, v254, 52
	v_add_u32_e32 v57, v175, v155
	v_readlane_b32 vcc_hi, v254, 53
	ds_read_b32 v180, v57 offset:35260
	s_waitcnt lgkmcnt(1)
	v_add_f32_e32 v50, v73, v50
	v_cndmask_b32_e32 v71, v218, v50, vcc
	v_add_u32_e32 v50, v175, v156
	ds_read_b32 v50, v50 offset:35260
	v_readlane_b32 vcc_lo, v254, 54
	v_readlane_b32 vcc_hi, v254, 55
	v_add_u32_e32 v73, v175, v151
	s_waitcnt lgkmcnt(0)
	v_add_f32_e32 v50, v58, v50
	v_cndmask_b32_e32 v57, v218, v50, vcc
	v_add_u32_e32 v50, v175, v154
	ds_read_b32 v50, v50 offset:35260
	v_add_u32_e32 v58, v175, v153
	ds_read_b32 v181, v58 offset:35260
	s_waitcnt lgkmcnt(1)
	v_add_f32_e32 v50, v59, v50
	v_cndmask_b32_e64 v72, v218, v50, s[44:45]
	v_add_u32_e32 v50, v175, v152
	ds_read_b32 v50, v50 offset:35260
	s_waitcnt lgkmcnt(1)
	v_pk_add_f32 v[58:59], v[74:75], v[180:181]
	ds_read_b32 v180, v73 offset:35260
	v_add_u32_e32 v75, v175, v147
	v_cndmask_b32_e64 v59, v218, v59, s[10:11]
	s_waitcnt lgkmcnt(1)
	v_add_f32_e32 v50, v60, v50
	v_cndmask_b32_e64 v73, v218, v50, s[50:51]
	v_add_u32_e32 v50, v175, v150
	ds_read_b32 v50, v50 offset:35260
	v_add_u32_e32 v60, v175, v149
	ds_read_b32 v181, v60 offset:35260
	v_cndmask_b32_e64 v58, v218, v58, s[12:13]
	s_waitcnt lgkmcnt(1)
	v_add_f32_e32 v50, v61, v50
	v_cndmask_b32_e64 v74, v218, v50, s[52:53]
	v_add_u32_e32 v50, v175, v148
	ds_read_b32 v50, v50 offset:35260
	s_waitcnt lgkmcnt(1)
	v_pk_add_f32 v[60:61], v[76:77], v[180:181]
	ds_read_b32 v180, v75 offset:35260
	v_add_u32_e32 v77, v175, v143
	v_cndmask_b32_e64 v61, v218, v61, s[14:15]
	s_waitcnt lgkmcnt(1)
	v_add_f32_e32 v50, v62, v50
	v_cndmask_b32_e64 v75, v218, v50, s[58:59]
	v_add_u32_e32 v50, v175, v146
	ds_read_b32 v50, v50 offset:35260
	v_add_u32_e32 v62, v175, v145
	ds_read_b32 v181, v62 offset:35260
	v_cndmask_b32_e64 v60, v218, v60, s[16:17]
	s_waitcnt lgkmcnt(1)
	v_add_f32_e32 v50, v63, v50
	v_cndmask_b32_e64 v76, v218, v50, s[60:61]
	v_add_u32_e32 v50, v175, v144
	ds_read_b32 v50, v50 offset:35260
	s_waitcnt lgkmcnt(1)
	v_pk_add_f32 v[62:63], v[78:79], v[180:181]
	ds_read_b32 v78, v77 offset:35260
	v_cndmask_b32_e64 v63, v218, v63, s[18:19]
	v_cndmask_b32_e64 v62, v218, v62, s[20:21]
	s_waitcnt lgkmcnt(1)
	v_add_f32_e32 v50, v64, v50
	v_add_u32_e32 v64, v175, v142
	v_cndmask_b32_e64 v77, v218, v50, s[66:67]
	s_waitcnt lgkmcnt(0)
	v_add_f32_e32 v50, v80, v78
	ds_read_b32 v64, v64 offset:35260
	v_add_u32_e32 v78, v175, v140
	ds_read_b32 v78, v78 offset:35260
	v_cndmask_b32_e64 v50, v218, v50, s[22:23]
	s_waitcnt lgkmcnt(1)
	v_add_f32_e32 v64, v65, v64
	v_cndmask_b32_e64 v65, v218, v64, s[70:71]
	s_waitcnt lgkmcnt(0)
	v_add_f32_e32 v64, v81, v78
	v_max_f32_e32 v78, v51, v82
	v_max3_f32 v78, v78, v83, v128
	v_max3_f32 v78, v78, v129, v54
	v_max3_f32 v78, v78, v55, v56
	v_max3_f32 v78, v78, v57, v72
	v_max3_f32 v78, v78, v73, v74
	v_max3_f32 v78, v78, v75, v76
	v_max3_f32 v78, v78, v77, v65
	v_max3_f32 v78, v78, v66, v67
	v_max3_f32 v78, v78, v68, v69
	v_max3_f32 v78, v78, v52, v53
	v_max3_f32 v78, v78, v70, v71
	v_max3_f32 v78, v78, v58, v59
	v_max3_f32 v78, v78, v60, v61
	v_cndmask_b32_e64 v64, v218, v64, s[30:31]
	v_max3_f32 v78, v78, v62, v63
	v_max3_f32 v78, v78, v50, v64
	v_mov_b32_e32 v79, v78
	s_nop 1
	v_permlane32_swap_b32_e32 v78, v79
	v_max_f32_e32 v79, v79, v79
	v_max_f32_e32 v78, v78, v78
	v_max_f32_e32 v79, v78, v79
	v_cmp_ge_f32_e32 vcc, s64, v79
	v_mov_b32_e32 v78, 1.0
	s_cmp_eq_u64 vcc, exec
	s_cbranch_scc0 .LBB0_251

.LBB0_256:
	s_lshl_b32 s8, s92, 6
	s_lshl_b32 s8, s8, 1
	s_add_u32 s8, s34, s8
	s_addc_u32 s9, s35, 0
	s_add_u32 s74, s8, 0x1800
	s_addc_u32 s75, s9, 0
	s_and_b64 vcc, exec, s[6:7]
	s_cbranch_vccz .LBB0_260
	s_and_saveexec_b64 s[8:9], s[76:77]
	ds_write_b32 v134, v128 offset:32768
	s_or_b64 exec, exec, s[8:9]
	s_waitcnt lgkmcnt(0)
	v_add_u32_e32 v105, v109, v119
	ds_read_b128 v[68:71], v105 offset:32768
	ds_read_b128 v[72:75], v105 offset:32800
	ds_read_b128 v[76:79], v105 offset:32832
	ds_read_b128 v[80:83], v105 offset:32864
	v_lshl_add_u32 v104, v108, 1, v120
	v_add_u32_e32 v104, v104, v122
	s_waitcnt lgkmcnt(0)
	v_rcp_f32_e32 v84, v68
	v_rcp_f32_e32 v85, v69
	v_rcp_f32_e32 v86, v70
	v_rcp_f32_e32 v87, v71
	v_rcp_f32_e32 v88, v72
	v_rcp_f32_e32 v89, v73
	v_rcp_f32_e32 v90, v74
	v_rcp_f32_e32 v91, v75
	v_rcp_f32_e32 v92, v76
	v_rcp_f32_e32 v93, v77
	v_rcp_f32_e32 v94, v78
	v_rcp_f32_e32 v95, v79
	v_rcp_f32_e32 v96, v80
	v_rcp_f32_e32 v97, v81
	v_rcp_f32_e32 v98, v82
	v_rcp_f32_e32 v99, v83
	s_waitcnt vmcnt(30)
	v_lshlrev_b32_e32 v228, 16, v228
	v_lshlrev_b32_e32 v229, 16, v229
	v_mul_f32_e32 v100, 0xbfb8aa3b, v228
	v_mul_f32_e32 v101, 0xbfb8aa3b, v229
	v_exp_f32_e32 v100, v100
	v_exp_f32_e32 v101, v101
	v_mul_f32_e32 v102, v2, v84
	v_mul_f32_e32 v103, v18, v84
	v_add_f32_e32 v100, 1.0, v100
	v_add_f32_e32 v101, 1.0, v101
	v_rcp_f32_e32 v100, v100
	v_rcp_f32_e32 v101, v101
	s_nop 0
	v_mul_f32_e32 v228, v100, v228
	v_mul_f32_e32 v229, v101, v229
	v_mul_f32_e32 v228, v102, v228
	v_mul_f32_e32 v229, v103, v229
	v_cvt_pk_bf16_f32 v228, v228, v228
	v_cvt_pk_bf16_f32 v229, v229, v229
	s_waitcnt vmcnt(28)
	v_lshlrev_b32_e32 v230, 16, v230
	v_lshlrev_b32_e32 v231, 16, v231
	v_mul_f32_e32 v100, 0xbfb8aa3b, v230
	v_mul_f32_e32 v101, 0xbfb8aa3b, v231
	v_exp_f32_e32 v100, v100
	v_exp_f32_e32 v101, v101
	v_mul_f32_e32 v102, v3, v85
	v_mul_f32_e32 v103, v19, v85
	v_add_f32_e32 v100, 1.0, v100
	v_add_f32_e32 v101, 1.0, v101
	v_rcp_f32_e32 v100, v100
	v_rcp_f32_e32 v101, v101
	s_nop 0
	v_mul_f32_e32 v230, v100, v230
	v_mul_f32_e32 v231, v101, v231
	v_mul_f32_e32 v230, v102, v230
	v_mul_f32_e32 v231, v103, v231
	v_cvt_pk_bf16_f32 v230, v230, v230
	v_cvt_pk_bf16_f32 v231, v231, v231
	s_waitcnt vmcnt(26)
	v_lshlrev_b32_e32 v232, 16, v232
	v_lshlrev_b32_e32 v233, 16, v233
	v_mul_f32_e32 v100, 0xbfb8aa3b, v232
	v_mul_f32_e32 v101, 0xbfb8aa3b, v233
	v_exp_f32_e32 v100, v100
	v_exp_f32_e32 v101, v101
	v_mul_f32_e32 v102, v4, v86
	v_mul_f32_e32 v103, v20, v86
	v_add_f32_e32 v100, 1.0, v100
	v_add_f32_e32 v101, 1.0, v101
	v_rcp_f32_e32 v100, v100
	v_rcp_f32_e32 v101, v101
	s_nop 0
	v_mul_f32_e32 v232, v100, v232
	v_mul_f32_e32 v233, v101, v233
	v_mul_f32_e32 v232, v102, v232
	v_mul_f32_e32 v233, v103, v233
	v_cvt_pk_bf16_f32 v232, v232, v232
	v_cvt_pk_bf16_f32 v233, v233, v233
	s_waitcnt vmcnt(24)
	v_lshlrev_b32_e32 v234, 16, v234
	v_lshlrev_b32_e32 v235, 16, v235
	v_mul_f32_e32 v100, 0xbfb8aa3b, v234
	v_mul_f32_e32 v101, 0xbfb8aa3b, v235
	v_exp_f32_e32 v100, v100
	v_exp_f32_e32 v101, v101
	v_mul_f32_e32 v102, v5, v87
	v_mul_f32_e32 v103, v21, v87
	v_add_f32_e32 v100, 1.0, v100
	v_add_f32_e32 v101, 1.0, v101
	v_rcp_f32_e32 v100, v100
	v_rcp_f32_e32 v101, v101
	s_nop 0
	v_mul_f32_e32 v234, v100, v234
	v_mul_f32_e32 v235, v101, v235
	v_mul_f32_e32 v234, v102, v234
	v_mul_f32_e32 v235, v103, v235
	v_cvt_pk_bf16_f32 v234, v234, v234
	v_cvt_pk_bf16_f32 v235, v235, v235
	s_waitcnt vmcnt(22)
	v_lshlrev_b32_e32 v236, 16, v236
	v_lshlrev_b32_e32 v237, 16, v237
	v_mul_f32_e32 v100, 0xbfb8aa3b, v236
	v_mul_f32_e32 v101, 0xbfb8aa3b, v237
	v_exp_f32_e32 v100, v100
	v_exp_f32_e32 v101, v101
	v_mul_f32_e32 v102, v6, v88
	v_mul_f32_e32 v103, v22, v88
	v_add_f32_e32 v100, 1.0, v100
	v_add_f32_e32 v101, 1.0, v101
	v_rcp_f32_e32 v100, v100
	v_rcp_f32_e32 v101, v101
	s_nop 0
	v_mul_f32_e32 v236, v100, v236
	v_mul_f32_e32 v237, v101, v237
	v_mul_f32_e32 v236, v102, v236
	v_mul_f32_e32 v237, v103, v237
	v_cvt_pk_bf16_f32 v236, v236, v236
	v_cvt_pk_bf16_f32 v237, v237, v237
	s_waitcnt vmcnt(20)
	v_lshlrev_b32_e32 v238, 16, v238
	v_lshlrev_b32_e32 v239, 16, v239
	v_mul_f32_e32 v100, 0xbfb8aa3b, v238
	v_mul_f32_e32 v101, 0xbfb8aa3b, v239
	v_exp_f32_e32 v100, v100
	v_exp_f32_e32 v101, v101
	v_mul_f32_e32 v102, v7, v89
	v_mul_f32_e32 v103, v23, v89
	v_add_f32_e32 v100, 1.0, v100
	v_add_f32_e32 v101, 1.0, v101
	v_rcp_f32_e32 v100, v100
	v_rcp_f32_e32 v101, v101
	s_nop 0
	v_mul_f32_e32 v238, v100, v238
	v_mul_f32_e32 v239, v101, v239
	v_mul_f32_e32 v238, v102, v238
	v_mul_f32_e32 v239, v103, v239
	v_cvt_pk_bf16_f32 v238, v238, v238
	v_cvt_pk_bf16_f32 v239, v239, v239
	s_waitcnt vmcnt(18)
	v_lshlrev_b32_e32 v240, 16, v240
	v_lshlrev_b32_e32 v241, 16, v241
	v_mul_f32_e32 v100, 0xbfb8aa3b, v240
	v_mul_f32_e32 v101, 0xbfb8aa3b, v241
	v_exp_f32_e32 v100, v100
	v_exp_f32_e32 v101, v101
	v_mul_f32_e32 v102, v8, v90
	v_mul_f32_e32 v103, v24, v90
	v_add_f32_e32 v100, 1.0, v100
	v_add_f32_e32 v101, 1.0, v101
	v_rcp_f32_e32 v100, v100
	v_rcp_f32_e32 v101, v101
	s_nop 0
	v_mul_f32_e32 v240, v100, v240
	v_mul_f32_e32 v241, v101, v241
	v_mul_f32_e32 v240, v102, v240
	v_mul_f32_e32 v241, v103, v241
	v_cvt_pk_bf16_f32 v240, v240, v240
	v_cvt_pk_bf16_f32 v241, v241, v241
	s_waitcnt vmcnt(16)
	v_lshlrev_b32_e32 v242, 16, v242
	v_lshlrev_b32_e32 v243, 16, v243
	v_mul_f32_e32 v100, 0xbfb8aa3b, v242
	v_mul_f32_e32 v101, 0xbfb8aa3b, v243
	v_exp_f32_e32 v100, v100
	v_exp_f32_e32 v101, v101
	v_mul_f32_e32 v102, v9, v91
	v_mul_f32_e32 v103, v25, v91
	v_add_f32_e32 v100, 1.0, v100
	v_add_f32_e32 v101, 1.0, v101
	v_rcp_f32_e32 v100, v100
	v_rcp_f32_e32 v101, v101
	s_nop 0
	v_mul_f32_e32 v242, v100, v242
	v_mul_f32_e32 v243, v101, v243
	v_mul_f32_e32 v242, v102, v242
	v_mul_f32_e32 v243, v103, v243
	v_cvt_pk_bf16_f32 v242, v242, v242
	v_cvt_pk_bf16_f32 v243, v243, v243
	s_waitcnt vmcnt(14)
	v_lshlrev_b32_e32 v244, 16, v244
	v_lshlrev_b32_e32 v245, 16, v245
	v_mul_f32_e32 v100, 0xbfb8aa3b, v244
	v_mul_f32_e32 v101, 0xbfb8aa3b, v245
	v_exp_f32_e32 v100, v100
	v_exp_f32_e32 v101, v101
	v_mul_f32_e32 v102, v10, v92
	v_mul_f32_e32 v103, v26, v92
	v_add_f32_e32 v100, 1.0, v100
	v_add_f32_e32 v101, 1.0, v101
	v_rcp_f32_e32 v100, v100
	v_rcp_f32_e32 v101, v101
	s_nop 0
	v_mul_f32_e32 v244, v100, v244
	v_mul_f32_e32 v245, v101, v245
	v_mul_f32_e32 v244, v102, v244
	v_mul_f32_e32 v245, v103, v245
	v_cvt_pk_bf16_f32 v244, v244, v244
	v_cvt_pk_bf16_f32 v245, v245, v245
	s_waitcnt vmcnt(12)
	v_lshlrev_b32_e32 v246, 16, v246
	v_lshlrev_b32_e32 v247, 16, v247
	v_mul_f32_e32 v100, 0xbfb8aa3b, v246
	v_mul_f32_e32 v101, 0xbfb8aa3b, v247
	v_exp_f32_e32 v100, v100
	v_exp_f32_e32 v101, v101
	v_mul_f32_e32 v102, v11, v93
	v_mul_f32_e32 v103, v27, v93
	v_add_f32_e32 v100, 1.0, v100
	v_add_f32_e32 v101, 1.0, v101
	v_rcp_f32_e32 v100, v100
	v_rcp_f32_e32 v101, v101
	s_nop 0
	v_mul_f32_e32 v246, v100, v246
	v_mul_f32_e32 v247, v101, v247
	v_mul_f32_e32 v246, v102, v246
	v_mul_f32_e32 v247, v103, v247
	v_cvt_pk_bf16_f32 v246, v246, v246
	v_cvt_pk_bf16_f32 v247, v247, v247
	s_waitcnt vmcnt(10)
	v_lshlrev_b32_e32 v248, 16, v248
	v_lshlrev_b32_e32 v249, 16, v249
	v_mul_f32_e32 v100, 0xbfb8aa3b, v248
	v_mul_f32_e32 v101, 0xbfb8aa3b, v249
	v_exp_f32_e32 v100, v100
	v_exp_f32_e32 v101, v101
	v_mul_f32_e32 v102, v12, v94
	v_mul_f32_e32 v103, v28, v94
	v_add_f32_e32 v100, 1.0, v100
	v_add_f32_e32 v101, 1.0, v101
	v_rcp_f32_e32 v100, v100
	v_rcp_f32_e32 v101, v101
	s_nop 0
	v_mul_f32_e32 v248, v100, v248
	v_mul_f32_e32 v249, v101, v249
	v_mul_f32_e32 v248, v102, v248
	v_mul_f32_e32 v249, v103, v249
	v_cvt_pk_bf16_f32 v248, v248, v248
	v_cvt_pk_bf16_f32 v249, v249, v249
	s_waitcnt vmcnt(8)
	v_lshlrev_b32_e32 v250, 16, v250
	v_lshlrev_b32_e32 v251, 16, v251
	v_mul_f32_e32 v100, 0xbfb8aa3b, v250
	v_mul_f32_e32 v101, 0xbfb8aa3b, v251
	v_exp_f32_e32 v100, v100
	v_exp_f32_e32 v101, v101
	v_mul_f32_e32 v102, v13, v95
	v_mul_f32_e32 v103, v29, v95
	v_add_f32_e32 v100, 1.0, v100
	v_add_f32_e32 v101, 1.0, v101
	v_rcp_f32_e32 v100, v100
	v_rcp_f32_e32 v101, v101
	s_nop 0
	v_mul_f32_e32 v250, v100, v250
	v_mul_f32_e32 v251, v101, v251
	v_mul_f32_e32 v250, v102, v250
	v_mul_f32_e32 v251, v103, v251
	v_cvt_pk_bf16_f32 v250, v250, v250
	v_cvt_pk_bf16_f32 v251, v251, v251
	s_waitcnt vmcnt(6)
	v_lshlrev_b32_e32 v252, 16, v252
	v_lshlrev_b32_e32 v253, 16, v253
	v_mul_f32_e32 v100, 0xbfb8aa3b, v252
	v_mul_f32_e32 v101, 0xbfb8aa3b, v253
	v_exp_f32_e32 v100, v100
	v_exp_f32_e32 v101, v101
	v_mul_f32_e32 v102, v14, v96
	v_mul_f32_e32 v103, v30, v96
	v_add_f32_e32 v100, 1.0, v100
	v_add_f32_e32 v101, 1.0, v101
	v_rcp_f32_e32 v100, v100
	v_rcp_f32_e32 v101, v101
	s_nop 0
	v_mul_f32_e32 v252, v100, v252
	v_mul_f32_e32 v253, v101, v253
	v_mul_f32_e32 v252, v102, v252
	v_mul_f32_e32 v253, v103, v253
	v_cvt_pk_bf16_f32 v252, v252, v252
	v_cvt_pk_bf16_f32 v253, v253, v253
	s_waitcnt vmcnt(4)
	v_lshlrev_b32_e32 v189, 16, v189
	v_lshlrev_b32_e32 v190, 16, v190
	v_mul_f32_e32 v100, 0xbfb8aa3b, v189
	v_mul_f32_e32 v101, 0xbfb8aa3b, v190
	v_exp_f32_e32 v100, v100
	v_exp_f32_e32 v101, v101
	v_mul_f32_e32 v102, v15, v97
	v_mul_f32_e32 v103, v31, v97
	v_add_f32_e32 v100, 1.0, v100
	v_add_f32_e32 v101, 1.0, v101
	v_rcp_f32_e32 v100, v100
	v_rcp_f32_e32 v101, v101
	s_nop 0
	v_mul_f32_e32 v189, v100, v189
	v_mul_f32_e32 v190, v101, v190
	v_mul_f32_e32 v189, v102, v189
	v_mul_f32_e32 v190, v103, v190
	v_cvt_pk_bf16_f32 v189, v189, v189
	v_cvt_pk_bf16_f32 v190, v190, v190
	s_waitcnt vmcnt(2)
	v_lshlrev_b32_e32 v191, 16, v191
	v_lshlrev_b32_e32 v192, 16, v192
	v_mul_f32_e32 v100, 0xbfb8aa3b, v191
	v_mul_f32_e32 v101, 0xbfb8aa3b, v192
	v_exp_f32_e32 v100, v100
	v_exp_f32_e32 v101, v101
	v_mul_f32_e32 v102, v16, v98
	v_mul_f32_e32 v103, v32, v98
	v_add_f32_e32 v100, 1.0, v100
	v_add_f32_e32 v101, 1.0, v101
	v_rcp_f32_e32 v100, v100
	v_rcp_f32_e32 v101, v101
	s_nop 0
	v_mul_f32_e32 v191, v100, v191
	v_mul_f32_e32 v192, v101, v192
	v_mul_f32_e32 v191, v102, v191
	v_mul_f32_e32 v192, v103, v192
	v_cvt_pk_bf16_f32 v191, v191, v191
	v_cvt_pk_bf16_f32 v192, v192, v192
	s_waitcnt vmcnt(0)
	v_lshlrev_b32_e32 v193, 16, v193
	v_lshlrev_b32_e32 v194, 16, v194
	v_mul_f32_e32 v100, 0xbfb8aa3b, v193
	v_mul_f32_e32 v101, 0xbfb8aa3b, v194
	v_exp_f32_e32 v100, v100
	v_exp_f32_e32 v101, v101
	v_mul_f32_e32 v102, v17, v99
	v_mul_f32_e32 v103, v33, v99
	v_add_f32_e32 v100, 1.0, v100
	v_add_f32_e32 v101, 1.0, v101
	v_rcp_f32_e32 v100, v100
	v_rcp_f32_e32 v101, v101
	s_nop 0
	v_mul_f32_e32 v193, v100, v193
	v_mul_f32_e32 v194, v101, v194
	v_mul_f32_e32 v193, v102, v193
	v_mul_f32_e32 v194, v103, v194
	v_cvt_pk_bf16_f32 v193, v193, v193
	v_cvt_pk_bf16_f32 v194, v194, v194
	s_mov_b32 s8, s74
	s_mov_b32 s9, s75
	global_store_short v104, v228, s[8:9] offset:0
	global_store_short v104, v229, s[8:9] offset:64
	s_add_u32 s8, s8, 0x2000
	s_addc_u32 s9, s9, 0
	global_store_short v104, v230, s[8:9] offset:0
	global_store_short v104, v231, s[8:9] offset:64
	s_add_u32 s8, s8, 0x2000
	s_addc_u32 s9, s9, 0
	global_store_short v104, v232, s[8:9] offset:0
	global_store_short v104, v233, s[8:9] offset:64
	s_add_u32 s8, s8, 0x2000
	s_addc_u32 s9, s9, 0
	global_store_short v104, v234, s[8:9] offset:0
	global_store_short v104, v235, s[8:9] offset:64
	s_add_u32 s8, s8, 0xa000
	s_addc_u32 s9, s9, 0
	global_store_short v104, v236, s[8:9] offset:0
	global_store_short v104, v237, s[8:9] offset:64
	s_add_u32 s8, s8, 0x2000
	s_addc_u32 s9, s9, 0
	global_store_short v104, v238, s[8:9] offset:0
	global_store_short v104, v239, s[8:9] offset:64
	s_add_u32 s8, s8, 0x2000
	s_addc_u32 s9, s9, 0
	global_store_short v104, v240, s[8:9] offset:0
	global_store_short v104, v241, s[8:9] offset:64
	s_add_u32 s8, s8, 0x2000
	s_addc_u32 s9, s9, 0
	global_store_short v104, v242, s[8:9] offset:0
	global_store_short v104, v243, s[8:9] offset:64
	s_add_u32 s8, s8, 0xa000
	s_addc_u32 s9, s9, 0
	global_store_short v104, v244, s[8:9] offset:0
	global_store_short v104, v245, s[8:9] offset:64
	s_add_u32 s8, s8, 0x2000
	s_addc_u32 s9, s9, 0
	global_store_short v104, v246, s[8:9] offset:0
	global_store_short v104, v247, s[8:9] offset:64
	s_add_u32 s8, s8, 0x2000
	s_addc_u32 s9, s9, 0
	global_store_short v104, v248, s[8:9] offset:0
	global_store_short v104, v249, s[8:9] offset:64
	s_add_u32 s8, s8, 0x2000
	s_addc_u32 s9, s9, 0
	global_store_short v104, v250, s[8:9] offset:0
	global_store_short v104, v251, s[8:9] offset:64
	s_add_u32 s8, s8, 0xa000
	s_addc_u32 s9, s9, 0
	global_store_short v104, v252, s[8:9] offset:0
	global_store_short v104, v253, s[8:9] offset:64
	s_add_u32 s8, s8, 0x2000
	s_addc_u32 s9, s9, 0
	global_store_short v104, v189, s[8:9] offset:0
	global_store_short v104, v190, s[8:9] offset:64
	s_add_u32 s8, s8, 0x2000
	s_addc_u32 s9, s9, 0
	global_store_short v104, v191, s[8:9] offset:0
	global_store_short v104, v192, s[8:9] offset:64
	s_add_u32 s8, s8, 0x2000
	s_addc_u32 s9, s9, 0
	global_store_short v104, v193, s[8:9] offset:0
	global_store_short v104, v194, s[8:9] offset:64
	s_branch .LBB0_164
